# m1dn: M1 dn (K^T w) split over all 512 threads with LDS combine; transposed-accumulator C stores (8 dwordx2); gate pre-pass
# baseline (speedup 1.0000x reference)
;   __host__ __device__ __forceinline__ float* G() const { return (float*)(wsl() + OFF_G); }
;   __host__ __device__ __forceinline__ float* dn() const { return (float*)(wsl() + OFF_DN); }
;   __host__ __device__ __forceinline__ bf16_t* R() const { return (bf16_t*)(wsl() + OFF_R); }
; __device__ __forceinline__ float bf2f(bf16_t h) { return __uint_as_float(((uint32_t)h) << 16); }
; __device__ __forceinline__ int obid() { int t = blockIdx.x; asm volatile("" : "+s"(t)); return t; }
; __device__ __forceinline__ void m1_phase(const Params& p, char* smem) {
;     ...
;   bf16_t* Kt = (bf16_t*)smem;
;   bf16_t* Vt = Kt + 128 * 72;
;   float* wv = (float*)(Vt + 128 * 72);
;   for (int it = obid(); it < NCHAIN * NCHUNK; it += gridDim.x) {
;     int ci = it / NCHUNK, j = it - ci * NCHUNK;
;     int dir = ci & 1, h = (ci >> 1) & 3, b = ci >> 3;
;     int rowbase = b * TPB;
;     if (w == 0) {
;       int row = rowbase + mchunk_tok(dir, j, lane);
;       float gi = p.G()[(size_t)row * 16 + (2 * dir) * 4 + h] + p.mlstm_gate_b[(2 * dir) * 4 + h];
;       float gf = p.G()[(size_t)row * 16 + (2 * dir + 1) * 4 + h] + p.mlstm_gate_b[(2 * dir + 1) * 4 + h];
;     ...
;     bf16_t* dC = p.R() + (size_t)it * 16384;
; #pragma unroll
;     for (int ni = 0; ni < 8; ++ni)
; #pragma unroll
;       for (int jj = 0; jj < 4; ++jj) dC[(w * 16 + fq * 4 + jj) * 128 + ni * 16 + fr] = f2bf(acc[ni][jj]);
;     if (tid < 128) {
;       float s = 0;
; #pragma unroll 8
;       for (int r = 0; r < 64; ++r) s += wv[r] * bf2f(Kt[tid * 72 + r]);
;       p.dn()[(size_t)it * 128 + tid] = s;
.LBB0_765:
	s_or_b64 exec, exec, s[4:5]
	s_mov_b32 s56, s82
	s_cmpk_gt_i32 s56, 0x83f
	s_cbranch_scc1 .LBB0_779
	s_waitcnt lgkmcnt(0)
	v_and_b32_e32 v1, 15, v8
	v_and_b32_e32 v0, 48, v10
	v_lshl_or_b32 v2, v18, 4, v1
	v_add_u32_e32 v0, 0, v0
	s_movk_i32 s4, 0x90
	v_mad_u64_u32 v[12:13], s[2:3], v2, s4, v[0:1]
	v_mul_lo_u32 v2, v8, s4
	v_add_u32_e32 v13, 0, v2
	v_ashrrev_i32_e32 v2, 3, v8
	v_and_b32_e32 v14, -8, v2
	s_movk_i32 s4, 0x48
	v_mul_lo_u32 v3, v14, s4
	v_lshl_add_u32 v11, v10, 2, 0
	v_or_b32_e32 v3, v3, v10
	v_or_b32_e32 v2, 7, v2
	v_lshl_add_u32 v38, v3, 1, 0
	v_mad_u64_u32 v[2:3], s[2:3], v2, s4, v[10:11]
	v_lshl_add_u32 v39, v2, 1, 0
	v_add_u32_e32 v2, 0x200, v8
	v_ashrrev_i32_e32 v2, 3, v2
	v_and_b32_e32 v16, -8, v2
	v_mul_lo_u32 v3, v16, s4
	v_or_b32_e32 v3, v3, v10
	v_or_b32_e32 v2, 7, v2
	v_lshl_add_u32 v40, v3, 1, 0
	v_mad_u64_u32 v[2:3], s[2:3], v2, s4, v[10:11]
	s_load_dwordx2 s[2:3], s[0:1], 0xf0
	v_lshl_add_u32 v41, v2, 1, 0
	v_lshlrev_b32_e32 v2, 5, v10
	v_lshlrev_b32_e32 v3, 11, v18
	s_movk_i32 s4, 0x600
	s_waitcnt lgkmcnt(0)
	s_add_u32 s58, s2, 0x7290000
	s_addc_u32 s59, s3, 0
	v_ashrrev_i32_e32 v9, 31, v8
	v_and_or_b32 v2, v2, s4, v3
	s_add_u32 s8, s2, 0xcd50000
	v_mul_u32_u24_e32 v4, 0x90, v1
	v_ashrrev_i32_e32 v19, 31, v2
	v_or_b32_e32 v20, v1, v2
	s_addc_u32 s9, s3, 0
	v_lshl_add_u64 v[2:3], v[8:9], 2, s[2:3]
	s_mov_b64 s[2:3], 0x113b7000
	v_cmp_gt_u32_e64 s[40:41], 64, v8
	v_cmp_eq_u32_e64 s[42:43], 0, v10
	v_cmp_gt_i32_e64 s[44:45], s85, v8
	v_cmp_gt_u32_e64 s[46:47], 2, v10
	v_cmp_gt_u32_e64 s[48:49], 4, v10
	v_cmp_gt_u32_e64 s[50:51], 8, v10
	v_cmp_gt_u32_e64 s[52:53], 16, v10
	v_cmp_gt_u32_e64 s[54:55], 32, v10
	v_ashrrev_i32_e32 v15, 31, v14
	v_ashrrev_i32_e32 v17, 31, v16
	v_ashrrev_i32_e32 v21, 31, v20
	v_lshl_add_u64 v[22:23], v[2:3], 0, s[2:3]
	v_mov_b32_e32 v18, v20
	v_or_b32_e32 v24, 16, v20
	v_mov_b32_e32 v25, v19
	v_or_b32_e32 v26, 32, v20
	v_mov_b32_e32 v27, v19
	v_or_b32_e32 v28, 48, v20
	v_mov_b32_e32 v29, v19
	v_or_b32_e32 v30, 64, v20
	v_mov_b32_e32 v31, v19
	v_or_b32_e32 v32, 0x50, v20
	v_mov_b32_e32 v33, v19
	v_or_b32_e32 v34, 0x60, v20
	v_mov_b32_e32 v35, v19
	v_or_b32_e32 v36, 0x70, v20
	v_mov_b32_e32 v37, v19
	v_add_u32_e32 v9, v0, v4
	v_lshrrev_b32_e32 v98, 7, v8
	v_and_b32_e32 v99, 0x7f, v8
	v_lshlrev_b32_e32 v127, 2, v99
	v_lshl_add_u32 v127, v98, 9, v127
	v_mul_u32_u24_e32 v99, 0x90, v99
	v_lshl_add_u32 v99, v98, 5, v99
	v_lshlrev_b32_e32 v98, 6, v98
	v_lshrrev_b32_e32 v79, 6, v8
	v_and_b32_e32 v78, 15, v10
	v_lshl_add_u32 v78, v79, 4, v78
	v_lshlrev_b32_e32 v78, 8, v78
	v_lshrrev_b32_e32 v79, 4, v10
	v_lshl_add_u32 v78, v79, 3, v78
	v_mov_b32_e32 v79, 0
	s_mov_b32 s61, 0
	v_readfirstlane_b32 s62, v8
	s_lshr_b32 s62, s62, 6
	s_mul_i32 s63, s62, s80
	s_add_i32 s63, s63, s56
	s_lshl_b32 s64, s62, 8

; __device__ __forceinline__ int obid() { int t = blockIdx.x; asm volatile("" : "+s"(t)); return t; }
; __device__ __forceinline__ void m1_phase(const Params& p, char* smem) {
;     ...
;   for (int it = obid(); it < NCHAIN * NCHUNK; it += gridDim.x) {
;     ...
;     __syncthreads();
.LBB0_767:
	s_or_b64 exec, exec, s[4:5]
	s_add_i32 s56, s56, s80
	s_addk_i32 s61, 0x100
	s_cmpk_gt_i32 s56, 0x83f
	s_cbranch_scc1 .LBB0_779

;   __host__ __device__ __forceinline__ bf16_t* ACT() const { return (bf16_t*)(wsl() + OFF_ACT); }
; __device__ __forceinline__ float bf2f(bf16_t h) { return __uint_as_float(((uint32_t)h) << 16); }
; __device__ __forceinline__ void m1_phase(const Params& p, char* smem) {
;     ...
; #pragma unroll
;     for (int i = 0; i < 2; ++i) {
;       int idx = tid + i * NTHR;
;       int r = idx & 63, fc = (idx >> 6) * 8;
;       int row = rowbase + mchunk_tok(dir, j, r);
;       const bf16_t* src = p.ACT() + (size_t)row * PW;
;       uint4 kv = *(const uint4*)(src + 1184 + h * 128 + fc);
;       uint4 vv = *(const uint4*)(src + 1696 + h * 128 + fc);
;       float wr = wv[r];
;       const bf16_t* ke = (const bf16_t*)&kv; const bf16_t* ve = (const bf16_t*)&vv;
; #pragma unroll
;       for (int e = 0; e < 8; ++e) {
;         Kt[(fc + e) * 72 + r] = ke[e];
;         Vt[(fc + e) * 72 + r] = f2bf(bf2f(ve[e]) * wr);
;       }
;     }
;     __syncthreads();
.LBB0_775:
	s_cmp_eq_u32 s13, 0
	s_cselect_b64 vcc, -1, 0
	s_cmp_gt_i32 s12, 3
	s_cselect_b32 s2, 0x87, 3
	s_sub_i32 s2, s2, s12
	s_lshl_b32 s2, s2, 6
	v_bitop3_b32 v0, s2, 63, v10 bitop3:0x36
	v_lshl_or_b32 v1, s12, 6, v10
	v_cndmask_b32_e32 v0, v0, v1, vcc
	v_add_u32_e32 v2, s11, v0
	v_mov_b64_e32 v[0:1], s[58:59]
	v_mad_i64_i32 v[0:1], s[2:3], v2, s84, v[0:1]
	s_lshl_b32 s30, s10, 8
	v_lshl_add_u64 v[44:45], v[0:1], 0, s[30:31]
	v_lshl_add_u64 v[4:5], v[14:15], 1, v[44:45]
	s_waitcnt vmcnt(0) lgkmcnt(0)
	s_barrier
	v_add_u32_e32 v74, s61, v11
	ds_read_b32 v42, v74 offset:36864
	global_load_dwordx4 v[0:3], v[4:5], off offset:2368
	s_nop 0
	global_load_dwordx4 v[4:7], v[4:5], off offset:3392
	s_ashr_i32 s57, s56, 31
	s_lshl_b64 s[2:3], s[56:57], 15
	s_add_u32 s4, s8, s2
	s_addc_u32 s5, s9, s3
	s_waitcnt vmcnt(1)
	ds_write_b16 v38, v0
	s_waitcnt vmcnt(0)
	v_lshlrev_b32_e32 v43, 16, v4
	s_waitcnt lgkmcnt(1)
	v_mul_f32_e32 v43, v42, v43
	v_bfe_u32 v46, v43, 16, 1
	v_add3_u32 v43, v43, v46, s28
	ds_write_b16_d16_hi v38, v43 offset:18432
	ds_write_b16_d16_hi v38, v0 offset:144
	v_and_b32_e32 v0, 0xffff0000, v4
	v_mul_f32_e32 v0, v42, v0
	v_bfe_u32 v4, v0, 16, 1
	v_add3_u32 v0, v0, v4, s28
	ds_write_b16_d16_hi v38, v0 offset:18576
	ds_write_b16 v38, v1 offset:288
	v_lshlrev_b32_e32 v0, 16, v5
	v_mul_f32_e32 v0, v42, v0
	v_bfe_u32 v4, v0, 16, 1
	v_add3_u32 v0, v0, v4, s28
	ds_write_b16_d16_hi v38, v0 offset:18720
	ds_write_b16_d16_hi v38, v1 offset:432
	v_and_b32_e32 v0, 0xffff0000, v5
	v_mul_f32_e32 v0, v42, v0
	v_bfe_u32 v1, v0, 16, 1
	v_add3_u32 v0, v0, v1, s28
	ds_write_b16_d16_hi v38, v0 offset:18864
	ds_write_b16 v38, v2 offset:576
	v_lshlrev_b32_e32 v0, 16, v6
	v_mul_f32_e32 v0, v42, v0
	v_bfe_u32 v1, v0, 16, 1
	v_add3_u32 v0, v0, v1, s28
	ds_write_b16_d16_hi v38, v0 offset:19008
	ds_write_b16_d16_hi v38, v2 offset:720
	v_and_b32_e32 v0, 0xffff0000, v6
	v_mul_f32_e32 v0, v42, v0
	v_bfe_u32 v1, v0, 16, 1
	v_add3_u32 v0, v0, v1, s28
	ds_write_b16_d16_hi v38, v0 offset:19152
	ds_write_b16 v38, v3 offset:864
	v_lshlrev_b32_e32 v0, 16, v7
	v_mul_f32_e32 v0, v42, v0
	v_bfe_u32 v1, v0, 16, 1
	v_add3_u32 v0, v0, v1, s28
	ds_write_b16_d16_hi v38, v0 offset:19296
	ds_write_b16_d16_hi v39, v3
	v_and_b32_e32 v0, 0xffff0000, v7
	v_mul_f32_e32 v0, v42, v0
	v_bfe_u32 v1, v0, 16, 1
	v_add3_u32 v0, v0, v1, s28
	ds_write_b16_d16_hi v39, v0 offset:18432
	v_lshl_add_u64 v[4:5], v[16:17], 1, v[44:45]
	global_load_dwordx4 v[0:3], v[4:5], off offset:2368
	s_nop 0
	global_load_dwordx4 v[4:7], v[4:5], off offset:3392
	s_waitcnt vmcnt(1)
	ds_write_b16 v40, v0
	s_waitcnt vmcnt(0)
	v_lshlrev_b32_e32 v43, 16, v4
	v_mul_f32_e32 v43, v42, v43
	v_bfe_u32 v44, v43, 16, 1
	v_add3_u32 v43, v43, v44, s28
	ds_write_b16_d16_hi v40, v43 offset:18432
	ds_write_b16_d16_hi v40, v0 offset:144
	v_and_b32_e32 v0, 0xffff0000, v4
	v_mul_f32_e32 v0, v42, v0
	v_bfe_u32 v4, v0, 16, 1
	v_add3_u32 v0, v0, v4, s28
	ds_write_b16_d16_hi v40, v0 offset:18576
	ds_write_b16 v40, v1 offset:288
	v_lshlrev_b32_e32 v0, 16, v5
	v_mul_f32_e32 v0, v42, v0
	v_bfe_u32 v4, v0, 16, 1
	v_add3_u32 v0, v0, v4, s28
	ds_write_b16_d16_hi v40, v0 offset:18720
	ds_write_b16_d16_hi v40, v1 offset:432
	v_and_b32_e32 v0, 0xffff0000, v5
	v_mul_f32_e32 v0, v42, v0
	v_bfe_u32 v1, v0, 16, 1
	v_add3_u32 v0, v0, v1, s28
	ds_write_b16_d16_hi v40, v0 offset:18864
	ds_write_b16 v40, v2 offset:576
	v_lshlrev_b32_e32 v0, 16, v6
	v_mul_f32_e32 v0, v42, v0
	v_bfe_u32 v1, v0, 16, 1
	v_add3_u32 v0, v0, v1, s28
	ds_write_b16_d16_hi v40, v0 offset:19008
	ds_write_b16_d16_hi v40, v2 offset:720
	v_and_b32_e32 v0, 0xffff0000, v6
	v_mul_f32_e32 v0, v42, v0
	v_bfe_u32 v1, v0, 16, 1
	v_add3_u32 v0, v0, v1, s28
	ds_write_b16_d16_hi v40, v0 offset:19152
	ds_write_b16 v40, v3 offset:864
	v_lshlrev_b32_e32 v0, 16, v7
	v_mul_f32_e32 v0, v42, v0
	v_bfe_u32 v1, v0, 16, 1
	v_add3_u32 v0, v0, v1, s28
	ds_write_b16_d16_hi v40, v0 offset:19296
	ds_write_b16_d16_hi v41, v3
	v_and_b32_e32 v0, 0xffff0000, v7
	v_mul_f32_e32 v0, v42, v0
	v_bfe_u32 v1, v0, 16, 1
	v_add3_u32 v0, v0, v1, s28
	ds_write_b16_d16_hi v41, v0 offset:18432
	s_waitcnt lgkmcnt(0)
	s_barrier
;   __host__ __device__ __forceinline__ float* dn() const { return (float*)(wsl() + OFF_DN); }
;   __host__ __device__ __forceinline__ bf16_t* R() const { return (bf16_t*)(wsl() + OFF_R); }
; __device__ __forceinline__ float bf2f(bf16_t h) { return __uint_as_float(((uint32_t)h) << 16); }
; #define MFMA16(a, b, c) __builtin_amdgcn_mfma_f32_16x16x32_bf16(a, b, c, 0, 0, 0)
; __device__ __forceinline__ void m1_phase(const Params& p, char* smem) {
;     ...
;     f32x4 acc[8];
; #pragma unroll
;     for (int ni = 0; ni < 8; ++ni) acc[ni] = (f32x4){0.f, 0.f, 0.f, 0.f};
; #pragma unroll
;     for (int ks = 0; ks < 2; ++ks) {
;       bf16x8 a = *(const bf16x8*)(Vt + (w * 16 + fr) * 72 + ks * 32 + fq * 8);
; #pragma unroll
;       for (int ni = 0; ni < 8; ++ni) {
;         bf16x8 bb = *(const bf16x8*)(Kt + (ni * 16 + fr) * 72 + ks * 32 + fq * 8);
;         acc[ni] = MFMA16(a, bb, acc[ni]);
;       }
;     }
;     bf16_t* dC = p.R() + (size_t)it * 16384;
; #pragma unroll
;     for (int ni = 0; ni < 8; ++ni)
; #pragma unroll
;       for (int jj = 0; jj < 4; ++jj) dC[(w * 16 + fq * 4 + jj) * 128 + ni * 16 + fr] = f2bf(acc[ni][jj]);
;     if (tid < 128) {
;       float s = 0;
; #pragma unroll 8
;       for (int r = 0; r < 64; ++r) s += wv[r] * bf2f(Kt[tid * 72 + r]);
;       p.dn()[(size_t)it * 128 + tid] = s;
;     }
;     __syncthreads();
	ds_read_b128 v[0:3], v12 offset:18432
	ds_read_b128 v[4:7], v9
	ds_read_b128 v[42:45], v9 offset:2304
	ds_read_b128 v[46:49], v9 offset:4608
	ds_read_b128 v[50:53], v9 offset:6912
	ds_read_b128 v[54:57], v9 offset:9216
	ds_read_b128 v[58:61], v9 offset:11520
	ds_read_b128 v[62:65], v9 offset:13824
	ds_read_b128 v[66:69], v9 offset:16128
	s_waitcnt lgkmcnt(7)
	v_mfma_f32_16x16x32_bf16 v[4:7], v[4:7], v[0:3], 0
	s_waitcnt lgkmcnt(6)
	v_mfma_f32_16x16x32_bf16 v[42:45], v[42:45], v[0:3], 0
	s_waitcnt lgkmcnt(5)
	v_mfma_f32_16x16x32_bf16 v[46:49], v[46:49], v[0:3], 0
	s_waitcnt lgkmcnt(4)
	v_mfma_f32_16x16x32_bf16 v[50:53], v[50:53], v[0:3], 0
	s_waitcnt lgkmcnt(3)
	v_mfma_f32_16x16x32_bf16 v[54:57], v[54:57], v[0:3], 0
	s_waitcnt lgkmcnt(2)
	v_mfma_f32_16x16x32_bf16 v[58:61], v[58:61], v[0:3], 0
	s_waitcnt lgkmcnt(1)
	v_mfma_f32_16x16x32_bf16 v[62:65], v[62:65], v[0:3], 0
	s_waitcnt lgkmcnt(0)
	v_mfma_f32_16x16x32_bf16 v[0:3], v[66:69], v[0:3], 0
	ds_read_b128 v[66:69], v12 offset:18496
	ds_read_b128 v[70:73], v9 offset:64
	s_waitcnt lgkmcnt(0)
	v_mfma_f32_16x16x32_bf16 v[4:7], v[70:73], v[66:69], v[4:7]
	ds_read_b128 v[70:73], v9 offset:2368
	s_waitcnt lgkmcnt(0)
	v_mfma_f32_16x16x32_bf16 v[42:45], v[70:73], v[66:69], v[42:45]
	ds_read_b128 v[70:73], v9 offset:4672
	s_waitcnt lgkmcnt(0)
	v_mfma_f32_16x16x32_bf16 v[46:49], v[70:73], v[66:69], v[46:49]
	ds_read_b128 v[70:73], v9 offset:6976
	s_waitcnt lgkmcnt(0)
	v_mfma_f32_16x16x32_bf16 v[50:53], v[70:73], v[66:69], v[50:53]
	ds_read_b128 v[70:73], v9 offset:9280
	s_waitcnt lgkmcnt(0)
	v_mfma_f32_16x16x32_bf16 v[54:57], v[70:73], v[66:69], v[54:57]
	ds_read_b128 v[70:73], v9 offset:11584
	s_waitcnt lgkmcnt(0)
	v_mfma_f32_16x16x32_bf16 v[58:61], v[70:73], v[66:69], v[58:61]
	ds_read_b128 v[70:73], v9 offset:13888
	s_waitcnt lgkmcnt(0)
	v_mfma_f32_16x16x32_bf16 v[62:65], v[70:73], v[66:69], v[62:65]
	ds_read_b128 v[70:73], v9 offset:16192
	s_waitcnt lgkmcnt(0)
	v_mfma_f32_16x16x32_bf16 v[0:3], v[70:73], v[66:69], v[0:3]
	v_lshl_add_u64 v[96:97], v[78:79], 0, s[4:5]
	v_cvt_pk_bf16_f32 v80, v4, v5
	v_cvt_pk_bf16_f32 v81, v6, v7
	v_cvt_pk_bf16_f32 v82, v42, v43
	v_cvt_pk_bf16_f32 v83, v44, v45
	v_cvt_pk_bf16_f32 v84, v46, v47
	v_cvt_pk_bf16_f32 v85, v48, v49
	v_cvt_pk_bf16_f32 v86, v50, v51
	v_cvt_pk_bf16_f32 v87, v52, v53
	v_cvt_pk_bf16_f32 v88, v54, v55
	v_cvt_pk_bf16_f32 v89, v56, v57
	v_cvt_pk_bf16_f32 v90, v58, v59
	v_cvt_pk_bf16_f32 v91, v60, v61
	v_cvt_pk_bf16_f32 v92, v62, v63
	v_cvt_pk_bf16_f32 v93, v64, v65
	v_cvt_pk_bf16_f32 v94, v0, v1
	v_cvt_pk_bf16_f32 v95, v2, v3
	global_store_dwordx2 v[96:97], v[80:81], off offset:0
	global_store_dwordx2 v[96:97], v[82:83], off offset:32
	global_store_dwordx2 v[96:97], v[84:85], off offset:64
	global_store_dwordx2 v[96:97], v[86:87], off offset:96
	global_store_dwordx2 v[96:97], v[88:89], off offset:128
	global_store_dwordx2 v[96:97], v[90:91], off offset:160
	global_store_dwordx2 v[96:97], v[92:93], off offset:192
	global_store_dwordx2 v[96:97], v[94:95], off offset:224
	v_add_u32_e32 v100, s61, v98
	ds_read_b128 v[102:105], v99
	ds_read_b128 v[106:109], v99 offset:16
	ds_read_b128 v[110:113], v100 offset:36864
	ds_read_b128 v[114:117], v100 offset:36880
	ds_read_b128 v[118:121], v100 offset:36896
	ds_read_b128 v[122:125], v100 offset:36912
	s_waitcnt lgkmcnt(0)
	v_lshlrev_b32_e32 v101, 16, v102
	v_mul_f32_e32 v126, v110, v101
	v_and_b32_e32 v101, 0xffff0000, v102
	v_fmac_f32_e32 v126, v111, v101
	v_lshlrev_b32_e32 v101, 16, v103
	v_fmac_f32_e32 v126, v112, v101
	v_and_b32_e32 v101, 0xffff0000, v103
	v_fmac_f32_e32 v126, v113, v101
	v_lshlrev_b32_e32 v101, 16, v104
	v_fmac_f32_e32 v126, v114, v101
	v_and_b32_e32 v101, 0xffff0000, v104
	v_fmac_f32_e32 v126, v115, v101
	v_lshlrev_b32_e32 v101, 16, v105
	v_fmac_f32_e32 v126, v116, v101
	v_and_b32_e32 v101, 0xffff0000, v105
	v_fmac_f32_e32 v126, v117, v101
	v_lshlrev_b32_e32 v101, 16, v106
	v_fmac_f32_e32 v126, v118, v101
	v_and_b32_e32 v101, 0xffff0000, v106
	v_fmac_f32_e32 v126, v119, v101
	v_lshlrev_b32_e32 v101, 16, v107
	v_fmac_f32_e32 v126, v120, v101
	v_and_b32_e32 v101, 0xffff0000, v107
	v_fmac_f32_e32 v126, v121, v101
	v_lshlrev_b32_e32 v101, 16, v108
	v_fmac_f32_e32 v126, v122, v101
	v_and_b32_e32 v101, 0xffff0000, v108
	v_fmac_f32_e32 v126, v123, v101
	v_lshlrev_b32_e32 v101, 16, v109
	v_fmac_f32_e32 v126, v124, v101
	v_and_b32_e32 v101, 0xffff0000, v109
	v_fmac_f32_e32 v126, v125, v101
	ds_write_b32 v127, v126 offset:41472
	s_waitcnt lgkmcnt(0)
	s_barrier
	s_and_saveexec_b64 s[4:5], s[44:45]
	s_cbranch_execz .LBB0_767
	ds_read_b32 v102, v127 offset:41472
	ds_read_b32 v103, v127 offset:41984
	ds_read_b32 v104, v127 offset:42496
	ds_read_b32 v105, v127 offset:43008
	s_lshl_b64 s[2:3], s[56:57], 9
	v_lshl_add_u64 v[2:3], v[22:23], 0, s[2:3]
	s_waitcnt lgkmcnt(2)
	v_add_f32_e32 v102, v102, v103
	s_waitcnt lgkmcnt(0)
	v_add_f32_e32 v104, v104, v105
	v_add_f32_e32 v0, v102, v104
	global_store_dword v[2:3], v0, off
	s_branch .LBB0_767
